# F2 epilogue: all residual loads issued before any store, counted waits
# baseline (speedup 1.0000x reference)
.LBB0_440:
	v_lshl_or_b32 v178, s79, 8, v198
	v_lshl_add_u32 v180, s78, 8, v196
	v_ashrrev_i32_e32 v179, 31, v178
	v_lshlrev_b64 v[204:205], 1, v[178:179]
	v_ashrrev_i32_e32 v181, 31, v180
	v_lshl_add_u64 v[182:183], s[10:11], 0, v[204:205]
	v_lshlrev_b64 v[206:207], 12, v[180:181]
	v_lshl_add_u64 v[114:115], v[182:183], 0, v[206:207]
	global_load_dwordx4 v[200:203], v[114:115], off
	global_load_dwordx4 v[154:157], v[114:115], off offset:256
	v_or_b32_e32 v194, 16, v180
	v_ashrrev_i32_e32 v195, 31, v194
	v_or_b32_e32 v190, 32, v180
	v_lshlrev_b64 v[192:193], 12, v[194:195]
	v_ashrrev_i32_e32 v191, 31, v190
	v_or_b32_e32 v186, 48, v180
	v_lshl_add_u64 v[114:115], v[182:183], 0, v[192:193]
	v_lshlrev_b64 v[188:189], 12, v[190:191]
	v_ashrrev_i32_e32 v187, 31, v186
	global_load_dwordx4 v[142:145], v[114:115], off
	global_load_dwordx4 v[138:141], v[114:115], off offset:256
	v_lshl_add_u64 v[114:115], v[182:183], 0, v[188:189]
	v_lshlrev_b64 v[184:185], 12, v[186:187]
	global_load_dwordx4 v[126:129], v[114:115], off
	global_load_dwordx4 v[122:125], v[114:115], off offset:256
	v_lshl_add_u64 v[114:115], v[182:183], 0, v[184:185]
	global_load_dwordx4 v[118:121], v[114:115], off
	s_nop 0
	global_load_dwordx4 v[114:117], v[114:115], off offset:256
	s_mov_b32 s101, 0
	v_lshl_add_u64 v[250:251], v[182:183], 0, v[206:207]
	s_mov_b32 s100, 0x80000
	v_lshl_add_u64 v[252:253], v[250:251], 0, s[100:101]
	global_load_dwordx4 v[214:217], v[252:253], off
	global_load_dwordx4 v[222:225], v[252:253], off offset:256
	s_mov_b32 s100, 0x90000
	v_lshl_add_u64 v[252:253], v[250:251], 0, s[100:101]
	global_load_dwordx4 v[226:229], v[252:253], off
	global_load_dwordx4 v[230:233], v[252:253], off offset:256
	s_mov_b32 s100, 0xa0000
	v_lshl_add_u64 v[252:253], v[250:251], 0, s[100:101]
	global_load_dwordx4 v[234:237], v[252:253], off
	global_load_dwordx4 v[238:241], v[252:253], off offset:256
	s_mov_b32 s100, 0xb0000
	v_lshl_add_u64 v[252:253], v[250:251], 0, s[100:101]
	global_load_dwordx4 v[242:245], v[252:253], off
	global_load_dwordx4 v[246:249], v[252:253], off offset:256
	v_lshlrev_b64 v[208:209], 11, v[180:181]
	v_lshl_add_u64 v[208:209], v[208:209], 0, v[178:179]
	s_waitcnt vmcnt(15)
	v_cvt_f32_f16_e32 v210, v200
	v_cvt_f32_f16_sdwa v211, v200 dst_sel:DWORD dst_unused:UNUSED_PAD src0_sel:WORD_1
	v_cvt_f32_f16_e32 v200, v201
	v_cvt_f32_f16_sdwa v201, v201 dst_sel:DWORD dst_unused:UNUSED_PAD src0_sel:WORD_1
	v_pk_fma_f32 v[210:211], v[150:151], 0.5, v[210:211] op_sel_hi:[1,0,1]
	s_nop 0
	v_cvt_pk_f16_f32 v150, v210, v211
	v_pk_fma_f32 v[200:201], v[152:153], 0.5, v[200:201] op_sel_hi:[1,0,1]
	v_cvt_f32_f16_e32 v152, v202
	v_cvt_f32_f16_sdwa v153, v202 dst_sel:DWORD dst_unused:UNUSED_PAD src0_sel:WORD_1
	v_cvt_pk_f16_f32 v151, v200, v201
	v_pk_fma_f32 v[212:213], v[146:147], 0.5, v[152:153] op_sel_hi:[1,0,1]
	v_cvt_f32_f16_e32 v146, v203
	v_cvt_f32_f16_sdwa v147, v203 dst_sel:DWORD dst_unused:UNUSED_PAD src0_sel:WORD_1
	v_cvt_pk_f16_f32 v152, v212, v213
	v_pk_fma_f32 v[202:203], v[148:149], 0.5, v[146:147] op_sel_hi:[1,0,1]
	v_lshl_add_u64 v[146:147], s[12:13], 0, v[206:207]
	v_lshl_add_u64 v[204:205], v[146:147], 0, v[204:205]
	v_mov_b32_e32 v146, 0
	v_dot2c_f32_f16_e32 v146, v150, v150
	v_dot2c_f32_f16_e32 v146, v151, v151
	v_cvt_pk_f16_f32 v153, v202, v203
	v_dot2c_f32_f16_e32 v146, v152, v152
	global_store_dwordx4 v[204:205], v[150:153], off
	v_dot2c_f32_f16_e32 v146, v153, v153
	s_nop 0
	v_lshlrev_b64 v[150:151], 1, v[208:209]
	v_lshl_add_u64 v[152:153], s[16:17], 0, v[150:151]
	v_add_f32_e32 v168, 0, v146
	v_cvt_pk_bf16_f32 v146, v210, v211
	v_cvt_pk_bf16_f32 v147, v200, v201
	v_cvt_pk_bf16_f32 v148, v212, v213
	v_cvt_pk_bf16_f32 v149, v202, v203
	global_store_dwordx4 v[152:153], v[146:149], off
	v_or_b32_e32 v150, 0x100, v150
	s_nop 0
	s_waitcnt vmcnt(16)
	v_cvt_f32_f16_e32 v148, v155
	v_cvt_f32_f16_sdwa v149, v155 dst_sel:DWORD dst_unused:UNUSED_PAD src0_sel:WORD_1
	v_cvt_f32_f16_e32 v146, v154
	v_cvt_f32_f16_sdwa v147, v154 dst_sel:DWORD dst_unused:UNUSED_PAD src0_sel:WORD_1
	v_pk_fma_f32 v[148:149], v[136:137], 0.5, v[148:149] op_sel_hi:[1,0,1]
	v_cvt_f32_f16_e32 v136, v156
	v_cvt_f32_f16_sdwa v137, v156 dst_sel:DWORD dst_unused:UNUSED_PAD src0_sel:WORD_1
	v_pk_fma_f32 v[146:147], v[134:135], 0.5, v[146:147] op_sel_hi:[1,0,1]
	v_cvt_pk_f16_f32 v135, v148, v149
	v_cvt_pk_f16_f32 v134, v146, v147
	v_pk_fma_f32 v[152:153], v[130:131], 0.5, v[136:137] op_sel_hi:[1,0,1]
	v_cvt_f32_f16_e32 v130, v157
	v_cvt_f32_f16_sdwa v131, v157 dst_sel:DWORD dst_unused:UNUSED_PAD src0_sel:WORD_1
	v_cvt_pk_f16_f32 v136, v152, v153
	v_pk_fma_f32 v[154:155], v[132:133], 0.5, v[130:131] op_sel_hi:[1,0,1]
	v_mov_b32_e32 v130, 0
	v_dot2c_f32_f16_e32 v130, v134, v134
	v_dot2c_f32_f16_e32 v130, v135, v135
	v_cvt_pk_f16_f32 v137, v154, v155
	v_dot2c_f32_f16_e32 v130, v136, v136
	v_dot2c_f32_f16_e32 v130, v137, v137
	global_store_dwordx4 v[204:205], v[134:137], off offset:256
	s_nop 1
	v_add_f32_e32 v136, v168, v130
	v_cvt_pk_bf16_f32 v130, v146, v147
	v_cvt_pk_bf16_f32 v131, v148, v149
	v_lshl_add_u64 v[134:135], s[16:17], 0, v[150:151]
	v_cvt_pk_bf16_f32 v132, v152, v153
	v_cvt_pk_bf16_f32 v133, v154, v155
	global_store_dwordx4 v[134:135], v[130:133], off
	s_nop 1
	v_and_b32_e32 v131, 64, v218
	v_xor_b32_e32 v130, 16, v218
	v_add_u32_e32 v131, 64, v131
	v_cmp_lt_i32_e32 vcc, v130, v131
	s_nop 1
	v_cndmask_b32_e32 v130, v218, v130, vcc
	v_lshlrev_b32_e32 v146, 2, v130
	ds_bpermute_b32 v130, v146, v136
	s_waitcnt lgkmcnt(0)
	v_add_f32_e32 v132, v136, v130
	v_xor_b32_e32 v130, 32, v218
	v_cmp_lt_i32_e32 vcc, v130, v131
	s_nop 1
	v_cndmask_b32_e32 v130, v218, v130, vcc
	v_lshlrev_b32_e32 v147, 2, v130
	ds_bpermute_b32 v133, v147, v132
	v_lshl_add_u64 v[130:131], v[180:181], 3, s[14:15]
	s_and_saveexec_b64 s[24:25], s[4:5]
	s_cbranch_execz .LBB0_442
	s_waitcnt lgkmcnt(0)
	v_add_f32_e32 v132, v132, v133
	v_fma_f32 v132, v132, s33, 0.5
	v_trunc_f32_e32 v132, v132
	v_mul_f32_e32 v133, 0x2f800000, v132
	v_floor_f32_e32 v133, v133
	v_fmac_f32_e32 v132, 0xcf800000, v133
	v_cvt_u32_f32_e32 v132, v132
	v_cvt_u32_f32_e32 v133, v133
	global_atomic_add_x2 v[130:131], v[132:133], off
.LBB0_442:
	s_or_b64 exec, exec, s[24:25]
	s_waitcnt vmcnt(17)
	v_cvt_f32_f16_sdwa v137, v143 dst_sel:DWORD dst_unused:UNUSED_PAD src0_sel:WORD_1
	v_cvt_f32_f16_e32 v136, v143
	v_cvt_f32_f16_sdwa v135, v142 dst_sel:DWORD dst_unused:UNUSED_PAD src0_sel:WORD_1
	v_cvt_f32_f16_e32 v134, v142
	s_waitcnt lgkmcnt(0)
	v_lshlrev_b64 v[132:133], 11, v[194:195]
	v_pk_fma_f32 v[136:137], v[112:113], 0.5, v[136:137] op_sel_hi:[1,0,1]
	v_cvt_f32_f16_sdwa v113, v144 dst_sel:DWORD dst_unused:UNUSED_PAD src0_sel:WORD_1
	v_cvt_f32_f16_e32 v112, v144
	v_pk_fma_f32 v[134:135], v[110:111], 0.5, v[134:135] op_sel_hi:[1,0,1]
	v_cvt_pk_f16_f32 v111, v136, v137
	v_cvt_pk_f16_f32 v110, v134, v135
	v_pk_fma_f32 v[142:143], v[106:107], 0.5, v[112:113] op_sel_hi:[1,0,1]
	v_cvt_f32_f16_sdwa v107, v145 dst_sel:DWORD dst_unused:UNUSED_PAD src0_sel:WORD_1
	v_cvt_f32_f16_e32 v106, v145
	v_cvt_pk_f16_f32 v112, v142, v143
	v_lshl_add_u64 v[132:133], v[132:133], 0, v[178:179]
	v_pk_fma_f32 v[144:145], v[108:109], 0.5, v[106:107] op_sel_hi:[1,0,1]
	v_lshl_add_u64 v[106:107], s[12:13], 0, v[192:193]
	v_lshl_add_u64 v[148:149], v[178:179], 1, v[106:107]
	v_mov_b32_e32 v106, 0
	v_dot2c_f32_f16_e32 v106, v110, v110
	v_dot2c_f32_f16_e32 v106, v111, v111
	v_cvt_pk_f16_f32 v113, v144, v145
	v_dot2c_f32_f16_e32 v106, v112, v112
	global_store_dwordx4 v[148:149], v[110:113], off
	v_dot2c_f32_f16_e32 v106, v113, v113
	s_nop 0
	v_lshlrev_b64 v[110:111], 1, v[132:133]
	v_lshl_add_u64 v[112:113], s[16:17], 0, v[110:111]
	v_add_f32_e32 v150, 0, v106
	v_cvt_pk_bf16_f32 v106, v134, v135
	v_cvt_pk_bf16_f32 v107, v136, v137
	v_cvt_pk_bf16_f32 v108, v142, v143
	v_cvt_pk_bf16_f32 v109, v144, v145
	global_store_dwordx4 v[112:113], v[106:109], off
	v_or_b32_e32 v110, 0x100, v110
	s_nop 0
	s_waitcnt vmcnt(18)
	v_cvt_f32_f16_sdwa v109, v139 dst_sel:DWORD dst_unused:UNUSED_PAD src0_sel:WORD_1
	v_cvt_f32_f16_e32 v108, v139
	v_cvt_f32_f16_sdwa v107, v138 dst_sel:DWORD dst_unused:UNUSED_PAD src0_sel:WORD_1
	v_cvt_f32_f16_e32 v106, v138
	v_pk_fma_f32 v[108:109], v[104:105], 0.5, v[108:109] op_sel_hi:[1,0,1]
	v_cvt_f32_f16_sdwa v105, v140 dst_sel:DWORD dst_unused:UNUSED_PAD src0_sel:WORD_1
	v_cvt_f32_f16_e32 v104, v140
	v_pk_fma_f32 v[106:107], v[102:103], 0.5, v[106:107] op_sel_hi:[1,0,1]
	v_cvt_pk_f16_f32 v103, v108, v109
	v_cvt_pk_f16_f32 v102, v106, v107
	v_pk_fma_f32 v[112:113], v[98:99], 0.5, v[104:105] op_sel_hi:[1,0,1]
	v_cvt_f32_f16_sdwa v99, v141 dst_sel:DWORD dst_unused:UNUSED_PAD src0_sel:WORD_1
	v_cvt_f32_f16_e32 v98, v141
	v_cvt_pk_f16_f32 v104, v112, v113
	v_pk_fma_f32 v[132:133], v[100:101], 0.5, v[98:99] op_sel_hi:[1,0,1]
	v_mov_b32_e32 v98, 0
	v_dot2c_f32_f16_e32 v98, v102, v102
	v_dot2c_f32_f16_e32 v98, v103, v103
	v_cvt_pk_f16_f32 v105, v132, v133
	v_dot2c_f32_f16_e32 v98, v104, v104
	v_dot2c_f32_f16_e32 v98, v105, v105
	global_store_dwordx4 v[148:149], v[102:105], off offset:256
	s_nop 1
	v_add_f32_e32 v104, v150, v98
	v_cvt_pk_bf16_f32 v98, v106, v107
	v_lshl_add_u64 v[102:103], s[16:17], 0, v[110:111]
	v_cvt_pk_bf16_f32 v99, v108, v109
	v_cvt_pk_bf16_f32 v100, v112, v113
	v_cvt_pk_bf16_f32 v101, v132, v133
	global_store_dwordx4 v[102:103], v[98:101], off
	ds_bpermute_b32 v98, v146, v104
	s_waitcnt lgkmcnt(0)
	v_add_f32_e32 v98, v104, v98
	ds_bpermute_b32 v99, v147, v98
	s_and_saveexec_b64 s[24:25], s[4:5]
	s_cbranch_execz .LBB0_444
	s_waitcnt lgkmcnt(0)
	v_add_f32_e32 v98, v98, v99
	v_fma_f32 v98, v98, s33, 0.5
	v_trunc_f32_e32 v98, v98
	v_mul_f32_e32 v99, 0x2f800000, v98
	v_floor_f32_e32 v99, v99
	v_fmac_f32_e32 v98, 0xcf800000, v99
	v_cvt_u32_f32_e32 v98, v98
	v_cvt_u32_f32_e32 v99, v99
	global_atomic_add_x2 v[130:131], v[98:99], off offset:128
.LBB0_444:
	s_or_b64 exec, exec, s[24:25]
	v_add_u32_e32 v138, 0x80, v180
	v_ashrrev_i32_e32 v139, 31, v138
	v_add_u32_e32 v134, 0x90, v180
	v_lshlrev_b64 v[136:137], 12, v[138:139]
	v_ashrrev_i32_e32 v135, 31, v134
	s_waitcnt lgkmcnt(0)
	v_lshl_add_u64 v[98:99], v[182:183], 0, v[136:137]
	v_lshlrev_b64 v[132:133], 12, v[134:135]
	v_lshl_add_u64 v[98:99], v[182:183], 0, v[132:133]
	s_nop 0
	s_waitcnt vmcnt(19)
	v_cvt_f32_f16_sdwa v145, v127 dst_sel:DWORD dst_unused:UNUSED_PAD src0_sel:WORD_1
	v_cvt_f32_f16_e32 v144, v127
	v_cvt_f32_f16_sdwa v143, v126 dst_sel:DWORD dst_unused:UNUSED_PAD src0_sel:WORD_1
	v_cvt_f32_f16_e32 v142, v126
	v_lshlrev_b64 v[140:141], 11, v[190:191]
	v_pk_fma_f32 v[126:127], v[96:97], 0.5, v[144:145] op_sel_hi:[1,0,1]
	v_cvt_f32_f16_sdwa v97, v128 dst_sel:DWORD dst_unused:UNUSED_PAD src0_sel:WORD_1
	v_cvt_f32_f16_e32 v96, v128
	v_pk_fma_f32 v[142:143], v[94:95], 0.5, v[142:143] op_sel_hi:[1,0,1]
	v_cvt_pk_f16_f32 v95, v126, v127
	v_cvt_pk_f16_f32 v94, v142, v143
	v_pk_fma_f32 v[144:145], v[90:91], 0.5, v[96:97] op_sel_hi:[1,0,1]
	v_cvt_f32_f16_sdwa v91, v129 dst_sel:DWORD dst_unused:UNUSED_PAD src0_sel:WORD_1
	v_cvt_f32_f16_e32 v90, v129
	v_cvt_pk_f16_f32 v96, v144, v145
	v_lshl_add_u64 v[140:141], v[140:141], 0, v[178:179]
	v_pk_fma_f32 v[128:129], v[92:93], 0.5, v[90:91] op_sel_hi:[1,0,1]
	v_lshl_add_u64 v[90:91], s[12:13], 0, v[188:189]
	v_lshl_add_u64 v[148:149], v[178:179], 1, v[90:91]
	v_mov_b32_e32 v90, 0
	v_dot2c_f32_f16_e32 v90, v94, v94
	v_dot2c_f32_f16_e32 v90, v95, v95
	v_cvt_pk_f16_f32 v97, v128, v129
	v_dot2c_f32_f16_e32 v90, v96, v96
	global_store_dwordx4 v[148:149], v[94:97], off
	v_dot2c_f32_f16_e32 v90, v97, v97
	s_nop 0
	v_lshlrev_b64 v[94:95], 1, v[140:141]
	v_lshl_add_u64 v[96:97], s[16:17], 0, v[94:95]
	v_add_f32_e32 v150, 0, v90
	v_cvt_pk_bf16_f32 v90, v142, v143
	v_cvt_pk_bf16_f32 v91, v126, v127
	v_cvt_pk_bf16_f32 v92, v144, v145
	v_cvt_pk_bf16_f32 v93, v128, v129
	global_store_dwordx4 v[96:97], v[90:93], off
	v_or_b32_e32 v94, 0x100, v94
	s_nop 0
	s_waitcnt vmcnt(20)
	v_cvt_f32_f16_sdwa v93, v123 dst_sel:DWORD dst_unused:UNUSED_PAD src0_sel:WORD_1
	v_cvt_f32_f16_e32 v92, v123
	v_cvt_f32_f16_sdwa v91, v122 dst_sel:DWORD dst_unused:UNUSED_PAD src0_sel:WORD_1
	v_cvt_f32_f16_e32 v90, v122
	v_pk_fma_f32 v[92:93], v[88:89], 0.5, v[92:93] op_sel_hi:[1,0,1]
	v_cvt_f32_f16_sdwa v89, v124 dst_sel:DWORD dst_unused:UNUSED_PAD src0_sel:WORD_1
	v_cvt_f32_f16_e32 v88, v124
	v_pk_fma_f32 v[90:91], v[86:87], 0.5, v[90:91] op_sel_hi:[1,0,1]
	v_cvt_pk_f16_f32 v87, v92, v93
	v_cvt_pk_f16_f32 v86, v90, v91
	v_pk_fma_f32 v[96:97], v[82:83], 0.5, v[88:89] op_sel_hi:[1,0,1]
	v_cvt_f32_f16_sdwa v83, v125 dst_sel:DWORD dst_unused:UNUSED_PAD src0_sel:WORD_1
	v_cvt_f32_f16_e32 v82, v125
	v_cvt_pk_f16_f32 v88, v96, v97
	v_pk_fma_f32 v[122:123], v[84:85], 0.5, v[82:83] op_sel_hi:[1,0,1]
	v_mov_b32_e32 v82, 0
	v_dot2c_f32_f16_e32 v82, v86, v86
	v_dot2c_f32_f16_e32 v82, v87, v87
	v_cvt_pk_f16_f32 v89, v122, v123
	v_dot2c_f32_f16_e32 v82, v88, v88
	v_dot2c_f32_f16_e32 v82, v89, v89
	global_store_dwordx4 v[148:149], v[86:89], off offset:256
	s_nop 1
	v_add_f32_e32 v88, v150, v82
	v_cvt_pk_bf16_f32 v82, v90, v91
	v_lshl_add_u64 v[86:87], s[16:17], 0, v[94:95]
	v_cvt_pk_bf16_f32 v83, v92, v93
	v_cvt_pk_bf16_f32 v84, v96, v97
	v_cvt_pk_bf16_f32 v85, v122, v123
	global_store_dwordx4 v[86:87], v[82:85], off
	ds_bpermute_b32 v82, v146, v88
	s_waitcnt lgkmcnt(0)
	v_add_f32_e32 v82, v88, v82
	ds_bpermute_b32 v83, v147, v82
	s_and_saveexec_b64 s[24:25], s[4:5]
	s_cbranch_execz .LBB0_446
	s_waitcnt lgkmcnt(0)
	v_add_f32_e32 v82, v82, v83
	v_fma_f32 v82, v82, s33, 0.5
	v_trunc_f32_e32 v82, v82
	v_mul_f32_e32 v83, 0x2f800000, v82
	v_floor_f32_e32 v83, v83
	v_fmac_f32_e32 v82, 0xcf800000, v83
	v_cvt_u32_f32_e32 v82, v82
	v_cvt_u32_f32_e32 v83, v83
	global_atomic_add_x2 v[130:131], v[82:83], off offset:256
.LBB0_446:
	s_or_b64 exec, exec, s[24:25]
	s_waitcnt vmcnt(21)
	v_cvt_f32_f16_sdwa v87, v119 dst_sel:DWORD dst_unused:UNUSED_PAD src0_sel:WORD_1
	v_cvt_f32_f16_e32 v86, v119
	v_cvt_f32_f16_sdwa v85, v118 dst_sel:DWORD dst_unused:UNUSED_PAD src0_sel:WORD_1
	v_cvt_f32_f16_e32 v84, v118
	s_waitcnt lgkmcnt(0)
	v_lshlrev_b64 v[82:83], 11, v[186:187]
	v_pk_fma_f32 v[86:87], v[80:81], 0.5, v[86:87] op_sel_hi:[1,0,1]
	v_cvt_f32_f16_sdwa v81, v120 dst_sel:DWORD dst_unused:UNUSED_PAD src0_sel:WORD_1
	v_cvt_f32_f16_e32 v80, v120
	v_pk_fma_f32 v[84:85], v[78:79], 0.5, v[84:85] op_sel_hi:[1,0,1]
	v_cvt_pk_f16_f32 v79, v86, v87
	v_cvt_pk_f16_f32 v78, v84, v85
	v_pk_fma_f32 v[88:89], v[74:75], 0.5, v[80:81] op_sel_hi:[1,0,1]
	v_cvt_f32_f16_sdwa v75, v121 dst_sel:DWORD dst_unused:UNUSED_PAD src0_sel:WORD_1
	v_cvt_f32_f16_e32 v74, v121
	v_cvt_pk_f16_f32 v80, v88, v89
	v_lshl_add_u64 v[82:83], v[82:83], 0, v[178:179]
	v_pk_fma_f32 v[90:91], v[76:77], 0.5, v[74:75] op_sel_hi:[1,0,1]
	v_lshl_add_u64 v[74:75], s[12:13], 0, v[184:185]
	v_lshl_add_u64 v[92:93], v[178:179], 1, v[74:75]
	v_mov_b32_e32 v74, 0
	v_dot2c_f32_f16_e32 v74, v78, v78
	v_dot2c_f32_f16_e32 v74, v79, v79
	v_cvt_pk_f16_f32 v81, v90, v91
	v_dot2c_f32_f16_e32 v74, v80, v80
	global_store_dwordx4 v[92:93], v[78:81], off
	v_dot2c_f32_f16_e32 v74, v81, v81
	s_nop 0
	v_lshlrev_b64 v[78:79], 1, v[82:83]
	v_lshl_add_u64 v[80:81], s[16:17], 0, v[78:79]
	v_add_f32_e32 v94, 0, v74
	v_cvt_pk_bf16_f32 v74, v84, v85
	v_cvt_pk_bf16_f32 v75, v86, v87
	v_cvt_pk_bf16_f32 v76, v88, v89
	v_cvt_pk_bf16_f32 v77, v90, v91
	global_store_dwordx4 v[80:81], v[74:77], off
	v_or_b32_e32 v78, 0x100, v78
	s_nop 0
	s_waitcnt vmcnt(22)
	v_cvt_f32_f16_sdwa v77, v115 dst_sel:DWORD dst_unused:UNUSED_PAD src0_sel:WORD_1
	v_cvt_f32_f16_e32 v76, v115
	v_cvt_f32_f16_sdwa v75, v114 dst_sel:DWORD dst_unused:UNUSED_PAD src0_sel:WORD_1
	v_cvt_f32_f16_e32 v74, v114
	v_pk_fma_f32 v[76:77], v[72:73], 0.5, v[76:77] op_sel_hi:[1,0,1]
	v_cvt_f32_f16_sdwa v73, v116 dst_sel:DWORD dst_unused:UNUSED_PAD src0_sel:WORD_1
	v_cvt_f32_f16_e32 v72, v116
	v_pk_fma_f32 v[74:75], v[70:71], 0.5, v[74:75] op_sel_hi:[1,0,1]
	v_cvt_pk_f16_f32 v71, v76, v77
	v_cvt_pk_f16_f32 v70, v74, v75
	v_pk_fma_f32 v[80:81], v[66:67], 0.5, v[72:73] op_sel_hi:[1,0,1]
	v_cvt_f32_f16_sdwa v67, v117 dst_sel:DWORD dst_unused:UNUSED_PAD src0_sel:WORD_1
	v_cvt_f32_f16_e32 v66, v117
	v_cvt_pk_f16_f32 v72, v80, v81
	v_pk_fma_f32 v[82:83], v[68:69], 0.5, v[66:67] op_sel_hi:[1,0,1]
	v_mov_b32_e32 v66, 0
	v_dot2c_f32_f16_e32 v66, v70, v70
	v_dot2c_f32_f16_e32 v66, v71, v71
	v_cvt_pk_f16_f32 v73, v82, v83
	v_dot2c_f32_f16_e32 v66, v72, v72
	v_dot2c_f32_f16_e32 v66, v73, v73
	global_store_dwordx4 v[92:93], v[70:73], off offset:256
	s_nop 1
	v_add_f32_e32 v72, v94, v66
	v_cvt_pk_bf16_f32 v66, v74, v75
	v_lshl_add_u64 v[70:71], s[16:17], 0, v[78:79]
	v_cvt_pk_bf16_f32 v67, v76, v77
	v_cvt_pk_bf16_f32 v68, v80, v81
	v_cvt_pk_bf16_f32 v69, v82, v83
	global_store_dwordx4 v[70:71], v[66:69], off
	ds_bpermute_b32 v66, v146, v72
	s_waitcnt lgkmcnt(0)
	v_add_f32_e32 v66, v72, v66
	ds_bpermute_b32 v67, v147, v66
	s_and_saveexec_b64 s[24:25], s[4:5]
	s_cbranch_execz .LBB0_448
	s_waitcnt lgkmcnt(0)
	v_add_f32_e32 v66, v66, v67
	v_fma_f32 v66, v66, s33, 0.5
	v_trunc_f32_e32 v66, v66
	v_mul_f32_e32 v67, 0x2f800000, v66
	v_floor_f32_e32 v67, v67
	v_fmac_f32_e32 v66, 0xcf800000, v67
	v_cvt_u32_f32_e32 v66, v66
	v_cvt_u32_f32_e32 v67, v67
	global_atomic_add_x2 v[130:131], v[66:67], off offset:384
.LBB0_448:
	s_or_b64 exec, exec, s[24:25]
	v_add_u32_e32 v88, 0xa0, v180
	v_ashrrev_i32_e32 v89, 31, v88
	v_add_u32_e32 v84, 0xb0, v180
	v_lshlrev_b64 v[86:87], 12, v[88:89]
	v_ashrrev_i32_e32 v85, 31, v84
	s_waitcnt lgkmcnt(0)
	v_lshl_add_u64 v[66:67], v[182:183], 0, v[86:87]
	v_lshlrev_b64 v[82:83], 12, v[84:85]
	v_lshl_add_u64 v[66:67], v[182:183], 0, v[82:83]
	s_nop 0
	s_waitcnt vmcnt(23)
	v_cvt_f32_f16_sdwa v95, v215 dst_sel:DWORD dst_unused:UNUSED_PAD src0_sel:WORD_1
	v_cvt_f32_f16_e32 v94, v215
	v_cvt_f32_f16_sdwa v93, v214 dst_sel:DWORD dst_unused:UNUSED_PAD src0_sel:WORD_1
	v_cvt_f32_f16_e32 v92, v214
	v_lshlrev_b64 v[90:91], 11, v[138:139]
	v_pk_fma_f32 v[94:95], v[64:65], 0.5, v[94:95] op_sel_hi:[1,0,1]
	v_cvt_f32_f16_sdwa v65, v216 dst_sel:DWORD dst_unused:UNUSED_PAD src0_sel:WORD_1
	v_cvt_f32_f16_e32 v64, v216
	v_pk_fma_f32 v[92:93], v[62:63], 0.5, v[92:93] op_sel_hi:[1,0,1]
	v_cvt_pk_f16_f32 v63, v94, v95
	v_cvt_pk_f16_f32 v62, v92, v93
	v_pk_fma_f32 v[96:97], v[58:59], 0.5, v[64:65] op_sel_hi:[1,0,1]
	v_cvt_f32_f16_sdwa v59, v217 dst_sel:DWORD dst_unused:UNUSED_PAD src0_sel:WORD_1
	v_cvt_f32_f16_e32 v58, v217
	v_cvt_pk_f16_f32 v64, v96, v97
	v_lshl_add_u64 v[90:91], v[90:91], 0, v[178:179]
	v_pk_fma_f32 v[110:111], v[60:61], 0.5, v[58:59] op_sel_hi:[1,0,1]
	v_lshl_add_u64 v[58:59], s[12:13], 0, v[136:137]
	v_lshl_add_u64 v[112:113], v[178:179], 1, v[58:59]
	v_mov_b32_e32 v58, 0
	v_dot2c_f32_f16_e32 v58, v62, v62
	v_dot2c_f32_f16_e32 v58, v63, v63
	v_cvt_pk_f16_f32 v65, v110, v111
	v_dot2c_f32_f16_e32 v58, v64, v64
	global_store_dwordx4 v[112:113], v[62:65], off
	v_dot2c_f32_f16_e32 v58, v65, v65
	s_nop 0
	v_lshlrev_b64 v[62:63], 1, v[90:91]
	v_lshl_add_u64 v[64:65], s[16:17], 0, v[62:63]
	v_add_f32_e32 v114, 0, v58
	v_cvt_pk_bf16_f32 v58, v92, v93
	v_cvt_pk_bf16_f32 v59, v94, v95
	v_cvt_pk_bf16_f32 v60, v96, v97
	v_cvt_pk_bf16_f32 v61, v110, v111
	global_store_dwordx4 v[64:65], v[58:61], off
	v_or_b32_e32 v62, 0x100, v62
	s_waitcnt vmcnt(24)
	v_cvt_f32_f16_sdwa v61, v223 dst_sel:DWORD dst_unused:UNUSED_PAD src0_sel:WORD_1
	v_cvt_f32_f16_e32 v60, v223
	v_cvt_f32_f16_sdwa v59, v222 dst_sel:DWORD dst_unused:UNUSED_PAD src0_sel:WORD_1
	v_cvt_f32_f16_e32 v58, v222
	v_pk_fma_f32 v[60:61], v[56:57], 0.5, v[60:61] op_sel_hi:[1,0,1]
	v_cvt_f32_f16_sdwa v57, v224 dst_sel:DWORD dst_unused:UNUSED_PAD src0_sel:WORD_1
	v_cvt_f32_f16_e32 v56, v224
	v_pk_fma_f32 v[58:59], v[54:55], 0.5, v[58:59] op_sel_hi:[1,0,1]
	v_cvt_pk_f16_f32 v55, v60, v61
	v_cvt_pk_f16_f32 v54, v58, v59
	v_pk_fma_f32 v[64:65], v[50:51], 0.5, v[56:57] op_sel_hi:[1,0,1]
	v_cvt_f32_f16_sdwa v51, v225 dst_sel:DWORD dst_unused:UNUSED_PAD src0_sel:WORD_1
	v_cvt_f32_f16_e32 v50, v225
	v_cvt_pk_f16_f32 v56, v64, v65
	v_pk_fma_f32 v[90:91], v[52:53], 0.5, v[50:51] op_sel_hi:[1,0,1]
	v_mov_b32_e32 v50, 0
	v_dot2c_f32_f16_e32 v50, v54, v54
	v_dot2c_f32_f16_e32 v50, v55, v55
	v_cvt_pk_f16_f32 v57, v90, v91
	v_dot2c_f32_f16_e32 v50, v56, v56
	v_dot2c_f32_f16_e32 v50, v57, v57
	global_store_dwordx4 v[112:113], v[54:57], off offset:256
	s_nop 1
	v_add_f32_e32 v56, v114, v50
	v_cvt_pk_bf16_f32 v50, v58, v59
	v_lshl_add_u64 v[54:55], s[16:17], 0, v[62:63]
	v_cvt_pk_bf16_f32 v51, v60, v61
	v_cvt_pk_bf16_f32 v52, v64, v65
	v_cvt_pk_bf16_f32 v53, v90, v91
	global_store_dwordx4 v[54:55], v[50:53], off
	ds_bpermute_b32 v50, v146, v56
	s_waitcnt lgkmcnt(0)
	v_add_f32_e32 v50, v56, v50
	ds_bpermute_b32 v51, v147, v50
	s_and_saveexec_b64 s[24:25], s[4:5]
	s_cbranch_execz .LBB0_450
	s_waitcnt lgkmcnt(0)
	v_add_f32_e32 v50, v50, v51
	v_fma_f32 v50, v50, s33, 0.5
	v_trunc_f32_e32 v50, v50
	v_mul_f32_e32 v51, 0x2f800000, v50
	v_floor_f32_e32 v51, v51
	v_fmac_f32_e32 v50, 0xcf800000, v51
	v_cvt_u32_f32_e32 v50, v50
	v_cvt_u32_f32_e32 v51, v51
	global_atomic_add_x2 v[130:131], v[50:51], off offset:1024
.LBB0_450:
	s_or_b64 exec, exec, s[24:25]
	s_waitcnt vmcnt(25)
	v_cvt_f32_f16_sdwa v55, v227 dst_sel:DWORD dst_unused:UNUSED_PAD src0_sel:WORD_1
	v_cvt_f32_f16_e32 v54, v227
	v_cvt_f32_f16_sdwa v53, v226 dst_sel:DWORD dst_unused:UNUSED_PAD src0_sel:WORD_1
	v_cvt_f32_f16_e32 v52, v226
	s_waitcnt lgkmcnt(0)
	v_lshlrev_b64 v[50:51], 11, v[134:135]
	v_pk_fma_f32 v[54:55], v[48:49], 0.5, v[54:55] op_sel_hi:[1,0,1]
	v_cvt_f32_f16_sdwa v49, v228 dst_sel:DWORD dst_unused:UNUSED_PAD src0_sel:WORD_1
	v_cvt_f32_f16_e32 v48, v228
	v_pk_fma_f32 v[52:53], v[46:47], 0.5, v[52:53] op_sel_hi:[1,0,1]
	v_cvt_pk_f16_f32 v47, v54, v55
	v_cvt_pk_f16_f32 v46, v52, v53
	v_pk_fma_f32 v[56:57], v[42:43], 0.5, v[48:49] op_sel_hi:[1,0,1]
	v_cvt_f32_f16_sdwa v43, v229 dst_sel:DWORD dst_unused:UNUSED_PAD src0_sel:WORD_1
	v_cvt_f32_f16_e32 v42, v229
	v_cvt_pk_f16_f32 v48, v56, v57
	v_lshl_add_u64 v[50:51], v[50:51], 0, v[178:179]
	v_pk_fma_f32 v[58:59], v[44:45], 0.5, v[42:43] op_sel_hi:[1,0,1]
	v_lshl_add_u64 v[42:43], s[12:13], 0, v[132:133]
	v_lshl_add_u64 v[60:61], v[178:179], 1, v[42:43]
	v_mov_b32_e32 v42, 0
	v_dot2c_f32_f16_e32 v42, v46, v46
	v_dot2c_f32_f16_e32 v42, v47, v47
	v_cvt_pk_f16_f32 v49, v58, v59
	v_dot2c_f32_f16_e32 v42, v48, v48
	global_store_dwordx4 v[60:61], v[46:49], off
	v_dot2c_f32_f16_e32 v42, v49, v49
	s_nop 0
	v_lshlrev_b64 v[46:47], 1, v[50:51]
	v_lshl_add_u64 v[48:49], s[16:17], 0, v[46:47]
	v_add_f32_e32 v62, 0, v42
	v_cvt_pk_bf16_f32 v42, v52, v53
	v_cvt_pk_bf16_f32 v43, v54, v55
	v_cvt_pk_bf16_f32 v44, v56, v57
	v_cvt_pk_bf16_f32 v45, v58, v59
	global_store_dwordx4 v[48:49], v[42:45], off
	v_or_b32_e32 v46, 0x100, v46
	s_waitcnt vmcnt(26)
	v_cvt_f32_f16_sdwa v45, v231 dst_sel:DWORD dst_unused:UNUSED_PAD src0_sel:WORD_1
	v_cvt_f32_f16_e32 v44, v231
	v_cvt_f32_f16_sdwa v43, v230 dst_sel:DWORD dst_unused:UNUSED_PAD src0_sel:WORD_1
	v_cvt_f32_f16_e32 v42, v230
	v_pk_fma_f32 v[44:45], v[40:41], 0.5, v[44:45] op_sel_hi:[1,0,1]
	v_cvt_f32_f16_sdwa v41, v232 dst_sel:DWORD dst_unused:UNUSED_PAD src0_sel:WORD_1
	v_cvt_f32_f16_e32 v40, v232
	v_pk_fma_f32 v[42:43], v[38:39], 0.5, v[42:43] op_sel_hi:[1,0,1]
	v_cvt_pk_f16_f32 v39, v44, v45
	v_cvt_pk_f16_f32 v38, v42, v43
	v_pk_fma_f32 v[48:49], v[34:35], 0.5, v[40:41] op_sel_hi:[1,0,1]
	v_cvt_f32_f16_sdwa v35, v233 dst_sel:DWORD dst_unused:UNUSED_PAD src0_sel:WORD_1
	v_cvt_f32_f16_e32 v34, v233
	v_cvt_pk_f16_f32 v40, v48, v49
	v_pk_fma_f32 v[50:51], v[36:37], 0.5, v[34:35] op_sel_hi:[1,0,1]
	v_mov_b32_e32 v34, 0
	v_dot2c_f32_f16_e32 v34, v38, v38
	v_dot2c_f32_f16_e32 v34, v39, v39
	v_cvt_pk_f16_f32 v41, v50, v51
	v_dot2c_f32_f16_e32 v34, v40, v40
	v_dot2c_f32_f16_e32 v34, v41, v41
	global_store_dwordx4 v[60:61], v[38:41], off offset:256
	s_nop 1
	v_add_f32_e32 v40, v62, v34
	v_cvt_pk_bf16_f32 v34, v42, v43
	v_lshl_add_u64 v[38:39], s[16:17], 0, v[46:47]
	v_cvt_pk_bf16_f32 v35, v44, v45
	v_cvt_pk_bf16_f32 v36, v48, v49
	v_cvt_pk_bf16_f32 v37, v50, v51
	global_store_dwordx4 v[38:39], v[34:37], off
	ds_bpermute_b32 v34, v146, v40
	s_waitcnt lgkmcnt(0)
	v_add_f32_e32 v34, v40, v34
	ds_bpermute_b32 v35, v147, v34
	s_and_saveexec_b64 s[24:25], s[4:5]
	s_cbranch_execz .LBB0_452
	s_waitcnt lgkmcnt(0)
	v_add_f32_e32 v34, v34, v35
	v_fma_f32 v34, v34, s33, 0.5
	v_trunc_f32_e32 v34, v34
	v_mul_f32_e32 v35, 0x2f800000, v34
	v_floor_f32_e32 v35, v35
	v_fmac_f32_e32 v34, 0xcf800000, v35
	v_cvt_u32_f32_e32 v34, v34
	v_cvt_u32_f32_e32 v35, v35
	global_atomic_add_x2 v[130:131], v[34:35], off offset:1152
.LBB0_452:
	s_or_b64 exec, exec, s[24:25]
	s_waitcnt vmcnt(27)
	v_cvt_f32_f16_sdwa v39, v235 dst_sel:DWORD dst_unused:UNUSED_PAD src0_sel:WORD_1
	v_cvt_f32_f16_e32 v38, v235
	v_cvt_f32_f16_sdwa v37, v234 dst_sel:DWORD dst_unused:UNUSED_PAD src0_sel:WORD_1
	v_cvt_f32_f16_e32 v36, v234
	s_waitcnt lgkmcnt(0)
	v_lshlrev_b64 v[34:35], 11, v[88:89]
	v_pk_fma_f32 v[38:39], v[32:33], 0.5, v[38:39] op_sel_hi:[1,0,1]
	v_cvt_f32_f16_sdwa v33, v236 dst_sel:DWORD dst_unused:UNUSED_PAD src0_sel:WORD_1
	v_cvt_f32_f16_e32 v32, v236
	v_pk_fma_f32 v[36:37], v[30:31], 0.5, v[36:37] op_sel_hi:[1,0,1]
	v_cvt_pk_f16_f32 v31, v38, v39
	v_cvt_pk_f16_f32 v30, v36, v37
	v_pk_fma_f32 v[40:41], v[26:27], 0.5, v[32:33] op_sel_hi:[1,0,1]
	v_cvt_f32_f16_sdwa v27, v237 dst_sel:DWORD dst_unused:UNUSED_PAD src0_sel:WORD_1
	v_cvt_f32_f16_e32 v26, v237
	v_cvt_pk_f16_f32 v32, v40, v41
	v_lshl_add_u64 v[34:35], v[34:35], 0, v[178:179]
	v_pk_fma_f32 v[42:43], v[28:29], 0.5, v[26:27] op_sel_hi:[1,0,1]
	v_lshl_add_u64 v[26:27], s[12:13], 0, v[86:87]
	v_lshl_add_u64 v[44:45], v[178:179], 1, v[26:27]
	v_mov_b32_e32 v26, 0
	v_dot2c_f32_f16_e32 v26, v30, v30
	v_dot2c_f32_f16_e32 v26, v31, v31
	v_cvt_pk_f16_f32 v33, v42, v43
	v_dot2c_f32_f16_e32 v26, v32, v32
	global_store_dwordx4 v[44:45], v[30:33], off
	v_dot2c_f32_f16_e32 v26, v33, v33
	s_nop 0
	v_lshlrev_b64 v[30:31], 1, v[34:35]
	v_lshl_add_u64 v[32:33], s[16:17], 0, v[30:31]
	v_add_f32_e32 v46, 0, v26
	v_cvt_pk_bf16_f32 v26, v36, v37
	v_cvt_pk_bf16_f32 v27, v38, v39
	v_cvt_pk_bf16_f32 v28, v40, v41
	v_cvt_pk_bf16_f32 v29, v42, v43
	global_store_dwordx4 v[32:33], v[26:29], off
	v_or_b32_e32 v30, 0x100, v30
	s_waitcnt vmcnt(28)
	v_cvt_f32_f16_sdwa v29, v239 dst_sel:DWORD dst_unused:UNUSED_PAD src0_sel:WORD_1
	v_cvt_f32_f16_e32 v28, v239
	v_cvt_f32_f16_sdwa v27, v238 dst_sel:DWORD dst_unused:UNUSED_PAD src0_sel:WORD_1
	v_cvt_f32_f16_e32 v26, v238
	v_pk_fma_f32 v[28:29], v[24:25], 0.5, v[28:29] op_sel_hi:[1,0,1]
	v_cvt_f32_f16_sdwa v25, v240 dst_sel:DWORD dst_unused:UNUSED_PAD src0_sel:WORD_1
	v_cvt_f32_f16_e32 v24, v240
	v_pk_fma_f32 v[26:27], v[22:23], 0.5, v[26:27] op_sel_hi:[1,0,1]
	v_cvt_pk_f16_f32 v23, v28, v29
	v_cvt_pk_f16_f32 v22, v26, v27
	v_pk_fma_f32 v[32:33], v[18:19], 0.5, v[24:25] op_sel_hi:[1,0,1]
	v_cvt_f32_f16_sdwa v19, v241 dst_sel:DWORD dst_unused:UNUSED_PAD src0_sel:WORD_1
	v_cvt_f32_f16_e32 v18, v241
	v_cvt_pk_f16_f32 v24, v32, v33
	v_pk_fma_f32 v[34:35], v[20:21], 0.5, v[18:19] op_sel_hi:[1,0,1]
	v_mov_b32_e32 v18, 0
	v_dot2c_f32_f16_e32 v18, v22, v22
	v_dot2c_f32_f16_e32 v18, v23, v23
	v_cvt_pk_f16_f32 v25, v34, v35
	v_dot2c_f32_f16_e32 v18, v24, v24
	v_dot2c_f32_f16_e32 v18, v25, v25
	global_store_dwordx4 v[44:45], v[22:25], off offset:256
	s_nop 1
	v_add_f32_e32 v24, v46, v18
	v_cvt_pk_bf16_f32 v18, v26, v27
	v_lshl_add_u64 v[22:23], s[16:17], 0, v[30:31]
	v_cvt_pk_bf16_f32 v19, v28, v29
	v_cvt_pk_bf16_f32 v20, v32, v33
	v_cvt_pk_bf16_f32 v21, v34, v35
	global_store_dwordx4 v[22:23], v[18:21], off
	ds_bpermute_b32 v18, v146, v24
	s_waitcnt lgkmcnt(0)
	v_add_f32_e32 v18, v24, v18
	ds_bpermute_b32 v19, v147, v18
	s_and_saveexec_b64 s[24:25], s[4:5]
	s_cbranch_execz .LBB0_454
	s_waitcnt lgkmcnt(0)
	v_add_f32_e32 v18, v18, v19
	v_fma_f32 v18, v18, s33, 0.5
	v_trunc_f32_e32 v18, v18
	v_mul_f32_e32 v19, 0x2f800000, v18
	v_floor_f32_e32 v19, v19
	v_fmac_f32_e32 v18, 0xcf800000, v19
	v_cvt_u32_f32_e32 v18, v18
	v_cvt_u32_f32_e32 v19, v19
	global_atomic_add_x2 v[130:131], v[18:19], off offset:1280
.LBB0_454:
	s_or_b64 exec, exec, s[24:25]
	s_waitcnt vmcnt(29)
	v_cvt_f32_f16_sdwa v23, v243 dst_sel:DWORD dst_unused:UNUSED_PAD src0_sel:WORD_1
	v_cvt_f32_f16_e32 v22, v243
	v_cvt_f32_f16_sdwa v21, v242 dst_sel:DWORD dst_unused:UNUSED_PAD src0_sel:WORD_1
	v_cvt_f32_f16_e32 v20, v242
	s_waitcnt lgkmcnt(0)
	v_lshlrev_b64 v[18:19], 11, v[84:85]
	v_pk_fma_f32 v[22:23], v[16:17], 0.5, v[22:23] op_sel_hi:[1,0,1]
	v_cvt_f32_f16_sdwa v17, v244 dst_sel:DWORD dst_unused:UNUSED_PAD src0_sel:WORD_1
	v_cvt_f32_f16_e32 v16, v244
	v_pk_fma_f32 v[20:21], v[14:15], 0.5, v[20:21] op_sel_hi:[1,0,1]
	v_cvt_pk_f16_f32 v15, v22, v23
	v_cvt_pk_f16_f32 v14, v20, v21
	v_pk_fma_f32 v[24:25], v[10:11], 0.5, v[16:17] op_sel_hi:[1,0,1]
	v_cvt_f32_f16_sdwa v11, v245 dst_sel:DWORD dst_unused:UNUSED_PAD src0_sel:WORD_1
	v_cvt_f32_f16_e32 v10, v245
	v_cvt_pk_f16_f32 v16, v24, v25
	v_lshl_add_u64 v[18:19], v[18:19], 0, v[178:179]
	v_pk_fma_f32 v[26:27], v[12:13], 0.5, v[10:11] op_sel_hi:[1,0,1]
	v_lshl_add_u64 v[10:11], s[12:13], 0, v[82:83]
	v_lshl_add_u64 v[28:29], v[178:179], 1, v[10:11]
	v_mov_b32_e32 v10, 0
	v_dot2c_f32_f16_e32 v10, v14, v14
	v_dot2c_f32_f16_e32 v10, v15, v15
	v_cvt_pk_f16_f32 v17, v26, v27
	v_dot2c_f32_f16_e32 v10, v16, v16
	global_store_dwordx4 v[28:29], v[14:17], off
	v_dot2c_f32_f16_e32 v10, v17, v17
	s_nop 0
	v_lshlrev_b64 v[14:15], 1, v[18:19]
	v_lshl_add_u64 v[16:17], s[16:17], 0, v[14:15]
	v_add_f32_e32 v30, 0, v10
	v_cvt_pk_bf16_f32 v10, v20, v21
	v_cvt_pk_bf16_f32 v11, v22, v23
	v_cvt_pk_bf16_f32 v12, v24, v25
	v_cvt_pk_bf16_f32 v13, v26, v27
	global_store_dwordx4 v[16:17], v[10:13], off
	v_or_b32_e32 v14, 0x100, v14
	s_waitcnt vmcnt(30)
	v_cvt_f32_f16_sdwa v13, v247 dst_sel:DWORD dst_unused:UNUSED_PAD src0_sel:WORD_1
	v_cvt_f32_f16_e32 v12, v247
	v_cvt_f32_f16_sdwa v11, v246 dst_sel:DWORD dst_unused:UNUSED_PAD src0_sel:WORD_1
	v_cvt_f32_f16_e32 v10, v246
	v_pk_fma_f32 v[12:13], v[8:9], 0.5, v[12:13] op_sel_hi:[1,0,1]
	v_cvt_f32_f16_sdwa v9, v248 dst_sel:DWORD dst_unused:UNUSED_PAD src0_sel:WORD_1
	v_cvt_f32_f16_e32 v8, v248
	v_pk_fma_f32 v[10:11], v[6:7], 0.5, v[10:11] op_sel_hi:[1,0,1]
	v_cvt_pk_f16_f32 v7, v12, v13
	v_cvt_pk_f16_f32 v6, v10, v11
	v_pk_fma_f32 v[16:17], v[2:3], 0.5, v[8:9] op_sel_hi:[1,0,1]
	v_cvt_f32_f16_sdwa v3, v249 dst_sel:DWORD dst_unused:UNUSED_PAD src0_sel:WORD_1
	v_cvt_f32_f16_e32 v2, v249
	v_cvt_pk_f16_f32 v8, v16, v17
	v_pk_fma_f32 v[18:19], v[4:5], 0.5, v[2:3] op_sel_hi:[1,0,1]
	v_mov_b32_e32 v2, 0
	v_dot2c_f32_f16_e32 v2, v6, v6
	v_dot2c_f32_f16_e32 v2, v7, v7
	v_cvt_pk_f16_f32 v9, v18, v19
	v_dot2c_f32_f16_e32 v2, v8, v8
	v_dot2c_f32_f16_e32 v2, v9, v9
	global_store_dwordx4 v[28:29], v[6:9], off offset:256
	s_nop 1
	v_add_f32_e32 v8, v30, v2
	v_cvt_pk_bf16_f32 v2, v10, v11
	v_lshl_add_u64 v[6:7], s[16:17], 0, v[14:15]
	v_cvt_pk_bf16_f32 v3, v12, v13
	v_cvt_pk_bf16_f32 v4, v16, v17
	v_cvt_pk_bf16_f32 v5, v18, v19
	global_store_dwordx4 v[6:7], v[2:5], off
	ds_bpermute_b32 v2, v146, v8
	s_waitcnt lgkmcnt(0)
	v_add_f32_e32 v2, v8, v2
	ds_bpermute_b32 v3, v147, v2
	s_and_saveexec_b64 s[24:25], s[4:5]
	s_cbranch_execz .LBB0_456
	s_waitcnt lgkmcnt(0)
	v_add_f32_e32 v2, v2, v3
	v_fma_f32 v2, v2, s33, 0.5
	v_trunc_f32_e32 v2, v2
	v_mul_f32_e32 v3, 0x2f800000, v2
	v_floor_f32_e32 v3, v3
	v_fmac_f32_e32 v2, 0xcf800000, v3
	v_cvt_u32_f32_e32 v2, v2
	v_cvt_u32_f32_e32 v3, v3
	global_atomic_add_x2 v[130:131], v[2:3], off offset:1408
